# code placement: GEMM K-loop heads pinned to 256-byte boundaries instead of 64 (stacked on v17)
# baseline (speedup 1.0000x reference)
; #define PG8_STAGE(bufoff, gbase, voff) do { _Pragma("unroll") for (int _i = 0; _i < 2; ++_i) \
;         __builtin_amdgcn_global_load_lds((const unsigned*)((const char*)(gbase) + (voff)[_i]), (LAS unsigned*)(lds + (bufoff) + ldsw + _i * 8192), 16, 0, 0); } while (0)
; #define PG8_LDA(dst, b, h) do { _Pragma("unroll") for (int m = 0; m < 4; ++m) _Pragma("unroll") for (int k = 0; k < 2; ++k) dst[m][k] = *(const LAS bf16x8*)(lds + PG8_SA(b, h) + aoff + m * 2048 + k * 1024); } while (0)
; #define PG8_LDB(dst, b, h) do { _Pragma("unroll") for (int n = 0; n < 2; ++n) _Pragma("unroll") for (int k = 0; k < 2; ++k) dst[n][k] = *(const LAS bf16x8*)(lds + PG8_SB(b, h) + boff + n * 2048 + k * 1024); } while (0)
; #define PG8_WAIT_V(n) asm volatile("s_waitcnt vmcnt(" #n ")" ::: "memory")
; #define PG8_WAIT_L(n) asm volatile("s_waitcnt lgkmcnt(" #n ")" ::: "memory")
; template <class Epi>
; DI void gemm_phase(int wv, LAS unsigned char* lds, const GemmD g, const Epi& E) {
;     ...
;         const bool has_next = S.next(ui + 1, nxt);
;         const char* nA = has_next ? (const char*)g.A + (size_t)nxt.pm * 256 * g.lda * 2 : cA; const char* nB = has_next ? (const char*)g.Bt + PG8_BROW(nxt.pn) * (size_t)g.ldb * 2 : cB;
;         for (int t = 0; t < nt; t += 2) {
;             const bool last = (t == nt - 2);
;             const char* a1 = cA + (size_t)(t + 1) * kstep;
;             const char* a2 = last ? nA : cA + (size_t)(t + 2) * kstep; const char* b2 = last ? nB : cB + (size_t)(t + 2) * kstep;
;             const char* a3 = a2 + kstep; const char* b3 = b2 + kstep;
;             PG8_LDB(B0, 0, 0); PG8_SCHED; PG8_LDA(At, 0, 0); PG8_STAGE(PG8_SA(1, 1), a1 + hstepA, voffA);
;             PG8_WAIT_L(8); PG8_BAR; PG8_WAIT_L(0); PG8_MMA(0, 0, At, B0); PG8_BAR; PG8_SCHED;
;             PG8_LDB(B1, 0, 1); PG8_STAGE(PG8_SB(0, 0), b2, voffB);
;             PG8_BAR; PG8_WAIT_L(0); PG8_MMA(0, 1, At, B1); PG8_BAR;
;             PG8_LDA(At, 0, 1); PG8_STAGE(PG8_SA(0, 0), a2, voffA);
;             PG8_BAR; PG8_WAIT_L(0); PG8_MMA(1, 0, At, B0); PG8_BAR; PG8_SCHED;
;             PG8_STAGE(PG8_SB(0, 1), b2 + hstepB, voffB);
;             PG8_WAIT_V(6); PG8_BAR; PG8_MMA(1, 1, At, B1); PG8_BAR;
;             PG8_LDB(B0, 1, 0); PG8_SCHED; PG8_LDA(At, 1, 0); PG8_STAGE(PG8_SA(0, 1), a2 + hstepA, voffA);
;             PG8_WAIT_L(8); PG8_BAR; PG8_WAIT_L(0); PG8_MMA(0, 0, At, B0); PG8_BAR; PG8_SCHED;
.LBB0_98:
	s_ashr_i32 s17, s16, 31
	s_lshl_b64 s[20:21], s[16:17], 19
	s_add_u32 s20, s6, s20
	s_addc_u32 s21, s7, s21
	s_and_b64 s[4:5], s[4:5], exec
	s_cselect_b32 s17, s21, s25
	s_cselect_b32 vcc_lo, s20, s24
	s_add_u32 s4, s24, 0x40080
	s_addc_u32 s5, s25, 0
	s_add_u32 vcc_hi, s22, 0x100
	s_addc_u32 s75, s23, 0
	s_mov_b32 s95, -2
	s_add_u32 s22, s4, 0xfffc0080
	s_addc_u32 s23, s5, -1
	s_add_i32 s3, 0, 0x10000
	v_add_u32_e32 v156, s3, v141
	ds_read_b128 v[144:147], v156
	ds_read_b128 v[148:151], v156 offset:1024
	ds_read_b128 v[152:155], v156 offset:2048
	ds_read_b128 v[156:159], v156 offset:3072
	s_cmp_eq_u32 s95, 12
	s_cselect_b32 s23, s17, s23
	s_cselect_b32 s22, vcc_lo, s22
	s_cselect_b32 s25, s19, s75
	s_cselect_b32 s24, s18, vcc_hi
	v_lshl_add_u64 v[164:165], s[4:5], 0, v[136:137]
	s_add_i32 m0, s15, 0xc000
	ds_read_b128 v[160:163], v143
	ds_read_b128 v[176:179], v143 offset:1024
	ds_read_b128 v[180:183], v143 offset:2048
	ds_read_b128 v[184:187], v143 offset:3072
	ds_read_b128 v[188:191], v143 offset:4096
	ds_read_b128 v[192:195], v143 offset:5120
	ds_read_b128 v[196:199], v143 offset:6144
	ds_read_b128 v[200:203], v143 offset:7168
	global_load_lds_dwordx4 v[164:165], off
	v_lshl_add_u64 v[164:165], s[4:5], 0, v[138:139]
	s_add_i32 m0, s15, 0xe000
	s_nop 0
	global_load_lds_dwordx4 v[164:165], off
	s_waitcnt lgkmcnt(8)
	s_barrier
	s_waitcnt lgkmcnt(0)
	s_waitcnt lgkmcnt(0)
	v_mfma_f32_16x16x32_bf16 v[126:129], v[144:147], v[160:163], 0
	v_mfma_f32_16x16x32_bf16 v[122:125], v[152:155], v[160:163], 0
	v_mfma_f32_16x16x32_bf16 v[118:121], v[144:147], v[180:183], 0
	v_mfma_f32_16x16x32_bf16 v[114:117], v[152:155], v[180:183], 0
	v_mfma_f32_16x16x32_bf16 v[102:105], v[144:147], v[188:191], 0
	v_mfma_f32_16x16x32_bf16 v[98:101], v[152:155], v[188:191], 0
	v_mfma_f32_16x16x32_bf16 v[86:89], v[144:147], v[196:199], 0
	v_mfma_f32_16x16x32_bf16 v[82:85], v[152:155], v[196:199], 0
	v_mfma_f32_16x16x32_bf16 v[126:129], v[148:151], v[176:179], v[126:129]
	v_mfma_f32_16x16x32_bf16 v[122:125], v[156:159], v[176:179], v[122:125]
	v_mfma_f32_16x16x32_bf16 v[118:121], v[148:151], v[184:187], v[118:121]
	v_mfma_f32_16x16x32_bf16 v[114:117], v[156:159], v[184:187], v[114:117]
	v_mfma_f32_16x16x32_bf16 v[102:105], v[148:151], v[192:195], v[102:105]
	v_mfma_f32_16x16x32_bf16 v[98:101], v[156:159], v[192:195], v[98:101]
	v_mfma_f32_16x16x32_bf16 v[86:89], v[148:151], v[200:203], v[86:89]
	v_mfma_f32_16x16x32_bf16 v[82:85], v[156:159], v[200:203], v[82:85]
	s_barrier
	s_add_i32 s2, 0, 0x14000
	v_add_u32_e32 v164, s2, v141
	s_add_i32 s3, s3, s37
	ds_read_b128 v[204:207], v164
	ds_read_b128 v[208:211], v164 offset:1024
	ds_read_b128 v[212:215], v164 offset:2048
	ds_read_b128 v[216:219], v164 offset:3072
	v_lshl_add_u64 v[164:165], s[24:25], 0, v[0:1]
	s_mov_b32 m0, s3
	v_lshl_add_u64 v[168:169], s[24:25], 0, v[130:131]
	global_load_lds_dwordx4 v[164:165], off
	s_add_i32 m0, s3, 0x2000
	s_nop 0
	global_load_lds_dwordx4 v[168:169], off
	s_barrier
	s_waitcnt lgkmcnt(0)
	s_waitcnt lgkmcnt(0)
	v_mfma_f32_16x16x32_bf16 v[110:113], v[204:207], v[160:163], 0
	v_mfma_f32_16x16x32_bf16 v[106:109], v[212:215], v[160:163], 0
	v_mfma_f32_16x16x32_bf16 v[94:97], v[204:207], v[180:183], 0
	v_mfma_f32_16x16x32_bf16 v[90:93], v[212:215], v[180:183], 0
	v_mfma_f32_16x16x32_bf16 v[78:81], v[204:207], v[188:191], 0
	v_mfma_f32_16x16x32_bf16 v[74:77], v[212:215], v[188:191], 0
	v_mfma_f32_16x16x32_bf16 v[70:73], v[204:207], v[196:199], 0
	v_mfma_f32_16x16x32_bf16 v[66:69], v[212:215], v[196:199], 0
	v_mfma_f32_16x16x32_bf16 v[110:113], v[208:211], v[176:179], v[110:113]
	v_mfma_f32_16x16x32_bf16 v[106:109], v[216:219], v[176:179], v[106:109]
	v_mfma_f32_16x16x32_bf16 v[94:97], v[208:211], v[184:187], v[94:97]
	v_mfma_f32_16x16x32_bf16 v[90:93], v[216:219], v[184:187], v[90:93]
	v_mfma_f32_16x16x32_bf16 v[78:81], v[208:211], v[192:195], v[78:81]
	v_mfma_f32_16x16x32_bf16 v[74:77], v[216:219], v[192:195], v[74:77]
	v_mfma_f32_16x16x32_bf16 v[70:73], v[208:211], v[200:203], v[70:73]
	v_mfma_f32_16x16x32_bf16 v[66:69], v[216:219], v[200:203], v[66:69]
	s_mov_b32 m0, s15
	v_lshl_add_u64 v[170:171], s[22:23], 0, v[134:135]
	s_barrier
	ds_read_b128 v[160:163], v143 offset:16384
	ds_read_b128 v[176:179], v143 offset:17408
	ds_read_b128 v[180:183], v143 offset:18432
	ds_read_b128 v[184:187], v143 offset:19456
	ds_read_b128 v[188:191], v143 offset:20480
	ds_read_b128 v[192:195], v143 offset:21504
	ds_read_b128 v[196:199], v143 offset:22528
	ds_read_b128 v[200:203], v143 offset:23552
	global_load_lds_dwordx4 v[170:171], off
	v_lshl_add_u64 v[220:221], s[22:23], 0, v[132:133]
	s_mov_b32 m0, s45
	s_nop 0
	global_load_lds_dwordx4 v[220:221], off
	s_barrier
	s_waitcnt lgkmcnt(0)
	s_waitcnt lgkmcnt(0)
	v_mfma_f32_16x16x32_bf16 v[62:65], v[144:147], v[160:163], 0
	v_mfma_f32_16x16x32_bf16 v[58:61], v[152:155], v[160:163], 0
	v_mfma_f32_16x16x32_bf16 v[54:57], v[144:147], v[180:183], 0
	v_mfma_f32_16x16x32_bf16 v[50:53], v[152:155], v[180:183], 0
	v_mfma_f32_16x16x32_bf16 v[38:41], v[144:147], v[188:191], 0
	v_mfma_f32_16x16x32_bf16 v[34:37], v[152:155], v[188:191], 0
	v_mfma_f32_16x16x32_bf16 v[22:25], v[144:147], v[196:199], 0
	v_mfma_f32_16x16x32_bf16 v[18:21], v[152:155], v[196:199], 0
	v_mfma_f32_16x16x32_bf16 v[62:65], v[148:151], v[176:179], v[62:65]
	v_mfma_f32_16x16x32_bf16 v[58:61], v[156:159], v[176:179], v[58:61]
	v_mfma_f32_16x16x32_bf16 v[54:57], v[148:151], v[184:187], v[54:57]
	v_mfma_f32_16x16x32_bf16 v[50:53], v[156:159], v[184:187], v[50:53]
	v_mfma_f32_16x16x32_bf16 v[38:41], v[148:151], v[192:195], v[38:41]
	v_mfma_f32_16x16x32_bf16 v[34:37], v[156:159], v[192:195], v[34:37]
	v_mfma_f32_16x16x32_bf16 v[22:25], v[148:151], v[200:203], v[22:25]
	v_mfma_f32_16x16x32_bf16 v[18:21], v[156:159], v[200:203], v[18:21]
	s_barrier
; #define PG8_STAGE(bufoff, gbase, voff) do { _Pragma("unroll") for (int _i = 0; _i < 2; ++_i) \
;         __builtin_amdgcn_global_load_lds((const unsigned*)((const char*)(gbase) + (voff)[_i]), (LAS unsigned*)(lds + (bufoff) + ldsw + _i * 8192), 16, 0, 0); } while (0)
; #define PG8_LDA(dst, b, h) do { _Pragma("unroll") for (int m = 0; m < 4; ++m) _Pragma("unroll") for (int k = 0; k < 2; ++k) dst[m][k] = *(const LAS bf16x8*)(lds + PG8_SA(b, h) + aoff + m * 2048 + k * 1024); } while (0)
; #define PG8_LDB(dst, b, h) do { _Pragma("unroll") for (int n = 0; n < 2; ++n) _Pragma("unroll") for (int k = 0; k < 2; ++k) dst[n][k] = *(const LAS bf16x8*)(lds + PG8_SB(b, h) + boff + n * 2048 + k * 1024); } while (0)
; #define PG8_MMA(ai, bj, At, Bt) do { __builtin_amdgcn_s_setprio(1); _Pragma("unroll") for (int m = 0; m < 4; ++m) _Pragma("unroll") for (int n = 0; n < 2; ++n) _Pragma("unroll") for (int k = 0; k < 2; ++k) \
;         acc[ai][bj][m][n] = __builtin_amdgcn_mfma_f32_16x16x32_bf16(Bt[n][k], At[m][k], acc[ai][bj][m][n], 0, 0, 0); __builtin_amdgcn_s_setprio(0); } while (0)
; #define PG8_WAIT_V(n) asm volatile("s_waitcnt vmcnt(" #n ")" ::: "memory")
; #define PG8_WAIT_L(n) asm volatile("s_waitcnt lgkmcnt(" #n ")" ::: "memory")
; #define PG8_BAR __builtin_amdgcn_s_barrier()
; #define PG8_SCHED __builtin_amdgcn_sched_barrier(0)
; template <class Epi>
; DI void gemm_phase(int wv, LAS unsigned char* lds, const GemmD g, const Epi& E) {
;     ...
;             PG8_STAGE(PG8_SB(0, 1), b2 + hstepB, voffB);
;             PG8_WAIT_V(6); PG8_BAR; PG8_MMA(1, 1, At, B1); PG8_BAR;
;             PG8_LDB(B0, 1, 0); PG8_SCHED; PG8_LDA(At, 1, 0); PG8_STAGE(PG8_SA(0, 1), a2 + hstepA, voffA);
;             PG8_WAIT_L(8); PG8_BAR; PG8_WAIT_L(0); PG8_MMA(0, 0, At, B0); PG8_BAR; PG8_SCHED;
;             PG8_LDB(B1, 1, 1); PG8_STAGE(PG8_SB(1, 0), b3, voffB);
;             PG8_BAR; PG8_WAIT_L(0); PG8_MMA(0, 1, At, B1); PG8_BAR;
;             PG8_LDA(At, 1, 1); PG8_STAGE(PG8_SA(1, 0), a3, voffA);
;             PG8_BAR; PG8_WAIT_L(0); PG8_MMA(1, 0, At, B0); PG8_BAR; PG8_SCHED;
	s_add_u32 s24, s24, s36
	s_addc_u32 s25, s25, 0
	s_add_i32 s2, s2, s37
	v_lshl_add_u64 v[222:223], s[24:25], 0, v[0:1]
	s_mov_b32 m0, s2
	v_lshl_add_u64 v[224:225], s[24:25], 0, v[130:131]
	global_load_lds_dwordx4 v[222:223], off
	s_add_i32 m0, s2, 0x2000
	s_nop 0
	global_load_lds_dwordx4 v[224:225], off
	s_waitcnt vmcnt(6)
	s_barrier
	v_mfma_f32_16x16x32_bf16 v[46:49], v[204:207], v[160:163], 0
	v_mfma_f32_16x16x32_bf16 v[42:45], v[212:215], v[160:163], 0
	v_mfma_f32_16x16x32_bf16 v[30:33], v[204:207], v[180:183], 0
	v_mfma_f32_16x16x32_bf16 v[26:29], v[212:215], v[180:183], 0
	v_mfma_f32_16x16x32_bf16 v[14:17], v[204:207], v[188:191], 0
	v_mfma_f32_16x16x32_bf16 v[10:13], v[212:215], v[188:191], 0
	v_mfma_f32_16x16x32_bf16 v[6:9], v[204:207], v[196:199], 0
	v_mfma_f32_16x16x32_bf16 v[2:5], v[212:215], v[196:199], 0
	v_mfma_f32_16x16x32_bf16 v[46:49], v[208:211], v[176:179], v[46:49]
	v_mfma_f32_16x16x32_bf16 v[42:45], v[216:219], v[176:179], v[42:45]
	v_mfma_f32_16x16x32_bf16 v[30:33], v[208:211], v[184:187], v[30:33]
	v_mfma_f32_16x16x32_bf16 v[26:29], v[216:219], v[184:187], v[26:29]
	v_mfma_f32_16x16x32_bf16 v[14:17], v[208:211], v[192:195], v[14:17]
	v_mfma_f32_16x16x32_bf16 v[10:13], v[216:219], v[192:195], v[10:13]
	v_mfma_f32_16x16x32_bf16 v[6:9], v[208:211], v[200:203], v[6:9]
	v_mfma_f32_16x16x32_bf16 v[2:5], v[216:219], v[200:203], v[2:5]
	s_add_i32 s2, 0, 0x18000
	v_add_u32_e32 v156, s2, v141
	s_barrier
	ds_read_b128 v[144:147], v156
	ds_read_b128 v[148:151], v156 offset:1024
	ds_read_b128 v[152:155], v156 offset:2048
	ds_read_b128 v[156:159], v156 offset:3072
	s_add_u32 s22, s22, 0x40000
	s_addc_u32 s23, s23, 0
	s_mov_b32 m0, s82
	v_lshl_add_u64 v[204:205], s[22:23], 0, v[134:135]
	ds_read_b128 v[160:163], v143 offset:32768
	ds_read_b128 v[176:179], v143 offset:33792
	ds_read_b128 v[180:183], v143 offset:34816
	ds_read_b128 v[184:187], v143 offset:35840
	ds_read_b128 v[188:191], v143 offset:36864
	ds_read_b128 v[192:195], v143 offset:37888
	ds_read_b128 v[196:199], v143 offset:38912
	ds_read_b128 v[200:203], v143 offset:39936
	global_load_lds_dwordx4 v[204:205], off
	v_lshl_add_u64 v[204:205], s[22:23], 0, v[132:133]
	s_mov_b32 m0, s83
	s_nop 0
	global_load_lds_dwordx4 v[204:205], off
	s_waitcnt lgkmcnt(8)
	s_barrier
	s_waitcnt lgkmcnt(0)
	s_waitcnt lgkmcnt(0)
	v_mfma_f32_16x16x32_bf16 v[126:129], v[144:147], v[160:163], v[126:129]
	v_mfma_f32_16x16x32_bf16 v[122:125], v[152:155], v[160:163], v[122:125]
	v_mfma_f32_16x16x32_bf16 v[118:121], v[144:147], v[180:183], v[118:121]
	v_mfma_f32_16x16x32_bf16 v[114:117], v[152:155], v[180:183], v[114:117]
	v_mfma_f32_16x16x32_bf16 v[102:105], v[144:147], v[188:191], v[102:105]
	v_mfma_f32_16x16x32_bf16 v[98:101], v[152:155], v[188:191], v[98:101]
	v_mfma_f32_16x16x32_bf16 v[86:89], v[144:147], v[196:199], v[86:89]
	v_mfma_f32_16x16x32_bf16 v[82:85], v[152:155], v[196:199], v[82:85]
	v_mfma_f32_16x16x32_bf16 v[126:129], v[148:151], v[176:179], v[126:129]
	v_mfma_f32_16x16x32_bf16 v[122:125], v[156:159], v[176:179], v[122:125]
	v_mfma_f32_16x16x32_bf16 v[118:121], v[148:151], v[184:187], v[118:121]
	v_mfma_f32_16x16x32_bf16 v[114:117], v[156:159], v[184:187], v[114:117]
	v_mfma_f32_16x16x32_bf16 v[102:105], v[148:151], v[192:195], v[102:105]
	v_mfma_f32_16x16x32_bf16 v[98:101], v[156:159], v[192:195], v[98:101]
	v_mfma_f32_16x16x32_bf16 v[86:89], v[148:151], v[200:203], v[86:89]
	v_mfma_f32_16x16x32_bf16 v[82:85], v[156:159], v[200:203], v[82:85]
	s_barrier
	s_add_i32 s3, 0, 0x1c000
	s_add_i32 s2, s2, s37
	v_add_u32_e32 v216, s3, v141
	v_lshl_add_u64 v[164:165], v[164:165], 0, s[58:59]
	s_mov_b32 m0, s2
	ds_read_b128 v[204:207], v216
	ds_read_b128 v[208:211], v216 offset:1024
	ds_read_b128 v[212:215], v216 offset:2048
	ds_read_b128 v[216:219], v216 offset:3072
	global_load_lds_dwordx4 v[164:165], off
	v_lshl_add_u64 v[164:165], v[168:169], 0, s[58:59]
	s_add_i32 m0, s2, 0x2000
	s_nop 0
	global_load_lds_dwordx4 v[164:165], off
	s_barrier
; #define PG8_STAGE(bufoff, gbase, voff) do { _Pragma("unroll") for (int _i = 0; _i < 2; ++_i) \
;         __builtin_amdgcn_global_load_lds((const unsigned*)((const char*)(gbase) + (voff)[_i]), (LAS unsigned*)(lds + (bufoff) + ldsw + _i * 8192), 16, 0, 0); } while (0)
; #define PG8_LDA(dst, b, h) do { _Pragma("unroll") for (int m = 0; m < 4; ++m) _Pragma("unroll") for (int k = 0; k < 2; ++k) dst[m][k] = *(const LAS bf16x8*)(lds + PG8_SA(b, h) + aoff + m * 2048 + k * 1024); } while (0)
; #define PG8_LDB(dst, b, h) do { _Pragma("unroll") for (int n = 0; n < 2; ++n) _Pragma("unroll") for (int k = 0; k < 2; ++k) dst[n][k] = *(const LAS bf16x8*)(lds + PG8_SB(b, h) + boff + n * 2048 + k * 1024); } while (0)
; #define PG8_MMA(ai, bj, At, Bt) do { __builtin_amdgcn_s_setprio(1); _Pragma("unroll") for (int m = 0; m < 4; ++m) _Pragma("unroll") for (int n = 0; n < 2; ++n) _Pragma("unroll") for (int k = 0; k < 2; ++k) \
;         acc[ai][bj][m][n] = __builtin_amdgcn_mfma_f32_16x16x32_bf16(Bt[n][k], At[m][k], acc[ai][bj][m][n], 0, 0, 0); __builtin_amdgcn_s_setprio(0); } while (0)
; #define PG8_WAIT_V(n) asm volatile("s_waitcnt vmcnt(" #n ")" ::: "memory")
; #define PG8_WAIT_L(n) asm volatile("s_waitcnt lgkmcnt(" #n ")" ::: "memory")
; #define PG8_BAR __builtin_amdgcn_s_barrier()
; #define PG8_SCHED __builtin_amdgcn_sched_barrier(0)
; template <class Epi>
; DI void gemm_phase(int wv, LAS unsigned char* lds, const GemmD g, const Epi& E) {
;     ...
;             PG8_WAIT_L(8); PG8_BAR; PG8_WAIT_L(0); PG8_MMA(0, 0, At, B0); PG8_BAR; PG8_SCHED;
;             PG8_LDB(B1, 1, 1); PG8_STAGE(PG8_SB(1, 0), b3, voffB);
;             PG8_BAR; PG8_WAIT_L(0); PG8_MMA(0, 1, At, B1); PG8_BAR;
;             PG8_LDA(At, 1, 1); PG8_STAGE(PG8_SA(1, 0), a3, voffA);
;             PG8_BAR; PG8_WAIT_L(0); PG8_MMA(1, 0, At, B0); PG8_BAR; PG8_SCHED;
;             PG8_STAGE(PG8_SB(1, 1), b3 + hstepB, voffB);
;             PG8_WAIT_V(6); PG8_BAR; PG8_MMA(1, 1, At, B1); PG8_BAR;
;         }
	s_waitcnt lgkmcnt(0)
	s_waitcnt lgkmcnt(0)
	v_mfma_f32_16x16x32_bf16 v[110:113], v[204:207], v[160:163], v[110:113]
	v_mfma_f32_16x16x32_bf16 v[106:109], v[212:215], v[160:163], v[106:109]
	v_mfma_f32_16x16x32_bf16 v[94:97], v[204:207], v[180:183], v[94:97]
	v_mfma_f32_16x16x32_bf16 v[90:93], v[212:215], v[180:183], v[90:93]
	v_mfma_f32_16x16x32_bf16 v[78:81], v[204:207], v[188:191], v[78:81]
	v_mfma_f32_16x16x32_bf16 v[74:77], v[212:215], v[188:191], v[74:77]
	v_mfma_f32_16x16x32_bf16 v[70:73], v[204:207], v[196:199], v[70:73]
	v_mfma_f32_16x16x32_bf16 v[66:69], v[212:215], v[196:199], v[66:69]
	v_mfma_f32_16x16x32_bf16 v[110:113], v[208:211], v[176:179], v[110:113]
	v_mfma_f32_16x16x32_bf16 v[106:109], v[216:219], v[176:179], v[106:109]
	v_mfma_f32_16x16x32_bf16 v[94:97], v[208:211], v[184:187], v[94:97]
	v_mfma_f32_16x16x32_bf16 v[90:93], v[216:219], v[184:187], v[90:93]
	v_mfma_f32_16x16x32_bf16 v[78:81], v[208:211], v[192:195], v[78:81]
	v_mfma_f32_16x16x32_bf16 v[74:77], v[216:219], v[192:195], v[74:77]
	v_mfma_f32_16x16x32_bf16 v[70:73], v[208:211], v[200:203], v[70:73]
	v_mfma_f32_16x16x32_bf16 v[66:69], v[216:219], v[200:203], v[66:69]
	s_mov_b32 m0, s84
	v_lshl_add_u64 v[164:165], v[170:171], 0, s[58:59]
	s_barrier
	ds_read_b128 v[160:163], v143 offset:49152
	ds_read_b128 v[176:179], v143 offset:50176
	ds_read_b128 v[180:183], v143 offset:51200
	ds_read_b128 v[184:187], v143 offset:52224
	ds_read_b128 v[188:191], v143 offset:53248
	ds_read_b128 v[192:195], v143 offset:54272
	ds_read_b128 v[196:199], v143 offset:55296
	ds_read_b128 v[200:203], v143 offset:56320
	global_load_lds_dwordx4 v[164:165], off
	v_lshl_add_u64 v[164:165], v[220:221], 0, s[58:59]
	s_mov_b32 m0, s85
	s_nop 0
	global_load_lds_dwordx4 v[164:165], off
	s_barrier
	s_waitcnt lgkmcnt(0)
	s_waitcnt lgkmcnt(0)
	v_mfma_f32_16x16x32_bf16 v[62:65], v[144:147], v[160:163], v[62:65]
	v_mfma_f32_16x16x32_bf16 v[58:61], v[152:155], v[160:163], v[58:61]
	v_mfma_f32_16x16x32_bf16 v[54:57], v[144:147], v[180:183], v[54:57]
	v_mfma_f32_16x16x32_bf16 v[50:53], v[152:155], v[180:183], v[50:53]
	v_mfma_f32_16x16x32_bf16 v[38:41], v[144:147], v[188:191], v[38:41]
	v_mfma_f32_16x16x32_bf16 v[34:37], v[152:155], v[188:191], v[34:37]
	v_mfma_f32_16x16x32_bf16 v[22:25], v[144:147], v[196:199], v[22:25]
	v_mfma_f32_16x16x32_bf16 v[18:21], v[152:155], v[196:199], v[18:21]
	v_mfma_f32_16x16x32_bf16 v[62:65], v[148:151], v[176:179], v[62:65]
	v_mfma_f32_16x16x32_bf16 v[58:61], v[156:159], v[176:179], v[58:61]
	v_mfma_f32_16x16x32_bf16 v[54:57], v[148:151], v[184:187], v[54:57]
	v_mfma_f32_16x16x32_bf16 v[50:53], v[156:159], v[184:187], v[50:53]
	v_mfma_f32_16x16x32_bf16 v[38:41], v[148:151], v[192:195], v[38:41]
	v_mfma_f32_16x16x32_bf16 v[34:37], v[156:159], v[192:195], v[34:37]
	v_mfma_f32_16x16x32_bf16 v[22:25], v[148:151], v[200:203], v[22:25]
	v_mfma_f32_16x16x32_bf16 v[18:21], v[156:159], v[200:203], v[18:21]
	s_barrier
	s_add_i32 s2, s3, s37
	v_lshl_add_u64 v[144:145], v[222:223], 0, s[58:59]
	s_mov_b32 m0, s2
	s_nop 0
	global_load_lds_dwordx4 v[144:145], off
	v_lshl_add_u64 v[144:145], v[224:225], 0, s[58:59]
	s_add_i32 m0, s2, 0x2000
	s_nop 0
	global_load_lds_dwordx4 v[144:145], off
	s_waitcnt vmcnt(6)
	s_barrier
	v_mfma_f32_16x16x32_bf16 v[46:49], v[204:207], v[160:163], v[46:49]
	v_mfma_f32_16x16x32_bf16 v[42:45], v[212:215], v[160:163], v[42:45]
	v_mfma_f32_16x16x32_bf16 v[30:33], v[204:207], v[180:183], v[30:33]
	v_mfma_f32_16x16x32_bf16 v[26:29], v[212:215], v[180:183], v[26:29]
	v_mfma_f32_16x16x32_bf16 v[14:17], v[204:207], v[188:191], v[14:17]
	v_mfma_f32_16x16x32_bf16 v[10:13], v[212:215], v[188:191], v[10:13]
	v_mfma_f32_16x16x32_bf16 v[6:9], v[204:207], v[196:199], v[6:9]
	v_mfma_f32_16x16x32_bf16 v[2:5], v[212:215], v[196:199], v[2:5]
	v_mfma_f32_16x16x32_bf16 v[46:49], v[208:211], v[176:179], v[46:49]
	v_mfma_f32_16x16x32_bf16 v[42:45], v[216:219], v[176:179], v[42:45]
	v_mfma_f32_16x16x32_bf16 v[30:33], v[208:211], v[184:187], v[30:33]
	v_mfma_f32_16x16x32_bf16 v[26:29], v[216:219], v[184:187], v[26:29]
	v_mfma_f32_16x16x32_bf16 v[14:17], v[208:211], v[192:195], v[14:17]
	v_mfma_f32_16x16x32_bf16 v[10:13], v[216:219], v[192:195], v[10:13]
	v_mfma_f32_16x16x32_bf16 v[6:9], v[208:211], v[200:203], v[6:9]
	v_mfma_f32_16x16x32_bf16 v[2:5], v[216:219], v[200:203], v[2:5]
	s_add_i32 s95, s95, 2
	s_add_u32 s4, s4, 0x100
	s_addc_u32 s5, s5, 0
	s_add_u32 vcc_hi, vcc_hi, 0x100
	s_addc_u32 s75, s75, 0
	s_cmp_gt_u32 s95, 13
	s_barrier
	s_cbranch_scc0 .LBB0_99
	s_branch .Lgemm_epi_a
	.p2align 8

; #define PG8_STAGE(bufoff, gbase, voff) do { _Pragma("unroll") for (int _i = 0; _i < 2; ++_i) \
;         __builtin_amdgcn_global_load_lds((const unsigned*)((const char*)(gbase) + (voff)[_i]), (LAS unsigned*)(lds + (bufoff) + ldsw + _i * 8192), 16, 0, 0); } while (0)
; #define PG8_LDA(dst, b, h) do { _Pragma("unroll") for (int m = 0; m < 4; ++m) _Pragma("unroll") for (int k = 0; k < 2; ++k) dst[m][k] = *(const LAS bf16x8*)(lds + PG8_SA(b, h) + aoff + m * 2048 + k * 1024); } while (0)
; #define PG8_LDB(dst, b, h) do { _Pragma("unroll") for (int n = 0; n < 2; ++n) _Pragma("unroll") for (int k = 0; k < 2; ++k) dst[n][k] = *(const LAS bf16x8*)(lds + PG8_SB(b, h) + boff + n * 2048 + k * 1024); } while (0)
; #define PG8_WAIT_V(n) asm volatile("s_waitcnt vmcnt(" #n ")" ::: "memory")
; #define PG8_WAIT_L(n) asm volatile("s_waitcnt lgkmcnt(" #n ")" ::: "memory")
; template <class Epi>
; DI void gemm_phase(int wv, LAS unsigned char* lds, const GemmD g, const Epi& E) {
;     ...
;         const bool has_next = S.next(ui + 1, nxt);
;         const char* nA = has_next ? (const char*)g.A + (size_t)nxt.pm * 256 * g.lda * 2 : cA; const char* nB = has_next ? (const char*)g.Bt + PG8_BROW(nxt.pn) * (size_t)g.ldb * 2 : cB;
;         for (int t = 0; t < nt; t += 2) {
;             const bool last = (t == nt - 2);
;             const char* a1 = cA + (size_t)(t + 1) * kstep;
;             const char* a2 = last ? nA : cA + (size_t)(t + 2) * kstep; const char* b2 = last ? nB : cB + (size_t)(t + 2) * kstep;
;             const char* a3 = a2 + kstep; const char* b3 = b2 + kstep;
;             PG8_LDB(B0, 0, 0); PG8_SCHED; PG8_LDA(At, 0, 0); PG8_STAGE(PG8_SA(1, 1), a1 + hstepA, voffA);
;             PG8_WAIT_L(8); PG8_BAR; PG8_WAIT_L(0); PG8_MMA(0, 0, At, B0); PG8_BAR; PG8_SCHED;
;             PG8_LDB(B1, 0, 1); PG8_STAGE(PG8_SB(0, 0), b2, voffB);
;             PG8_BAR; PG8_WAIT_L(0); PG8_MMA(0, 1, At, B1); PG8_BAR;
;             PG8_LDA(At, 0, 1); PG8_STAGE(PG8_SA(0, 0), a2, voffA);
;             PG8_BAR; PG8_WAIT_L(0); PG8_MMA(1, 0, At, B0); PG8_BAR; PG8_SCHED;
;             PG8_STAGE(PG8_SB(0, 1), b2 + hstepB, voffB);
;             PG8_WAIT_V(6); PG8_BAR; PG8_MMA(1, 1, At, B1); PG8_BAR;
;             PG8_LDB(B0, 1, 0); PG8_SCHED; PG8_LDA(At, 1, 0); PG8_STAGE(PG8_SA(0, 1), a2 + hstepA, voffA);
;             PG8_WAIT_L(8); PG8_BAR; PG8_WAIT_L(0); PG8_MMA(0, 0, At, B0); PG8_BAR; PG8_SCHED;
.LBB0_489:
	s_ashr_i32 s7, s6, 31
	v_cmp_lt_i64_e32 vcc, s[8:9], v[228:229]
	s_lshl_b64 s[8:9], s[6:7], 19
	s_add_u32 s8, s76, s8
	s_addc_u32 s9, s78, s9
	s_and_b64 s[16:17], vcc, exec
	s_cselect_b32 s7, s9, s27
	s_cselect_b32 s13, s8, s26
	s_lshl_b32 s16, s86, 8
	s_ashr_i32 s17, s16, 31
	s_lshl_b64 s[16:17], s[16:17], 11
	s_add_u32 s22, s39, s16
	s_addc_u32 s23, s40, s17
	s_and_b64 s[16:17], vcc, exec
	s_cselect_b32 s16, s23, s29
	s_cselect_b32 s17, s22, s28
	s_add_u32 s26, s26, 0x40080
	s_addc_u32 s27, s27, 0
	s_add_u32 s36, s28, 0x100
	s_addc_u32 s38, s29, 0
	s_mov_b32 s41, -2
	s_add_u32 s2, s26, 0xfffc0080
	s_addc_u32 s3, s27, -1
	s_add_i32 s18, 0, 0x10000
	v_add_u32_e32 v140, s18, v144
	ds_read_b128 v[148:151], v140
	ds_read_b128 v[152:155], v140 offset:1024
	ds_read_b128 v[156:159], v140 offset:2048
	ds_read_b128 v[160:163], v140 offset:3072
	s_cmp_eq_u32 s41, 12
	s_cselect_b32 s31, s7, s3
	s_cselect_b32 s30, s13, s2
	s_cselect_b32 s29, s16, s38
	s_cselect_b32 s28, s17, s36
	v_lshl_add_u64 v[140:141], s[26:27], 0, v[136:137]
	s_add_i32 m0, s25, 0xc000
	ds_read_b128 v[168:171], v146
	ds_read_b128 v[176:179], v146 offset:1024
	ds_read_b128 v[180:183], v146 offset:2048
	ds_read_b128 v[184:187], v146 offset:3072
	ds_read_b128 v[188:191], v146 offset:4096
	ds_read_b128 v[192:195], v146 offset:5120
	ds_read_b128 v[196:199], v146 offset:6144
	ds_read_b128 v[200:203], v146 offset:7168
	global_load_lds_dwordx4 v[140:141], off
	v_lshl_add_u64 v[140:141], s[26:27], 0, v[138:139]
	s_add_i32 m0, s25, 0xe000
	s_nop 0
	global_load_lds_dwordx4 v[140:141], off
	s_waitcnt lgkmcnt(8)
	s_barrier
	s_waitcnt lgkmcnt(0)
	s_waitcnt lgkmcnt(0)
	v_mfma_f32_16x16x32_bf16 v[126:129], v[148:151], v[168:171], 0
	v_mfma_f32_16x16x32_bf16 v[122:125], v[156:159], v[168:171], 0
	v_mfma_f32_16x16x32_bf16 v[110:113], v[148:151], v[180:183], 0
	v_mfma_f32_16x16x32_bf16 v[106:109], v[156:159], v[180:183], 0
	v_mfma_f32_16x16x32_bf16 v[94:97], v[148:151], v[188:191], 0
	v_mfma_f32_16x16x32_bf16 v[90:93], v[156:159], v[188:191], 0
	v_mfma_f32_16x16x32_bf16 v[78:81], v[148:151], v[196:199], 0
	v_mfma_f32_16x16x32_bf16 v[74:77], v[156:159], v[196:199], 0
	v_mfma_f32_16x16x32_bf16 v[126:129], v[152:155], v[176:179], v[126:129]
	v_mfma_f32_16x16x32_bf16 v[122:125], v[160:163], v[176:179], v[122:125]
	v_mfma_f32_16x16x32_bf16 v[110:113], v[152:155], v[184:187], v[110:113]
	v_mfma_f32_16x16x32_bf16 v[106:109], v[160:163], v[184:187], v[106:109]
	v_mfma_f32_16x16x32_bf16 v[94:97], v[152:155], v[192:195], v[94:97]
	v_mfma_f32_16x16x32_bf16 v[90:93], v[160:163], v[192:195], v[90:93]
	v_mfma_f32_16x16x32_bf16 v[78:81], v[152:155], v[200:203], v[78:81]
	v_mfma_f32_16x16x32_bf16 v[74:77], v[160:163], v[200:203], v[74:77]
	s_barrier
	s_add_i32 s2, 0, 0x14000
	v_add_u32_e32 v140, s2, v144
	s_add_i32 s3, s18, s79
	ds_read_b128 v[204:207], v140
	ds_read_b128 v[208:211], v140 offset:1024
	ds_read_b128 v[212:215], v140 offset:2048
	ds_read_b128 v[216:219], v140 offset:3072
	v_lshl_add_u64 v[140:141], s[28:29], 0, v[0:1]
	s_mov_b32 m0, s3
	v_lshl_add_u64 v[164:165], s[28:29], 0, v[134:135]
	global_load_lds_dwordx4 v[140:141], off
	s_add_i32 m0, s3, 0x2000
	s_nop 0
	global_load_lds_dwordx4 v[164:165], off
	s_barrier
	s_waitcnt lgkmcnt(0)
	s_waitcnt lgkmcnt(0)
	v_mfma_f32_16x16x32_bf16 v[118:121], v[204:207], v[168:171], 0
	v_mfma_f32_16x16x32_bf16 v[114:117], v[212:215], v[168:171], 0
	v_mfma_f32_16x16x32_bf16 v[102:105], v[204:207], v[180:183], 0
	v_mfma_f32_16x16x32_bf16 v[98:101], v[212:215], v[180:183], 0
	v_mfma_f32_16x16x32_bf16 v[86:89], v[204:207], v[188:191], 0
	v_mfma_f32_16x16x32_bf16 v[82:85], v[212:215], v[188:191], 0
	v_mfma_f32_16x16x32_bf16 v[70:73], v[204:207], v[196:199], 0
	v_mfma_f32_16x16x32_bf16 v[66:69], v[212:215], v[196:199], 0
	v_mfma_f32_16x16x32_bf16 v[118:121], v[208:211], v[176:179], v[118:121]
	v_mfma_f32_16x16x32_bf16 v[114:117], v[216:219], v[176:179], v[114:117]
	v_mfma_f32_16x16x32_bf16 v[102:105], v[208:211], v[184:187], v[102:105]
	v_mfma_f32_16x16x32_bf16 v[98:101], v[216:219], v[184:187], v[98:101]
	v_mfma_f32_16x16x32_bf16 v[86:89], v[208:211], v[192:195], v[86:89]
	v_mfma_f32_16x16x32_bf16 v[82:85], v[216:219], v[192:195], v[82:85]
	v_mfma_f32_16x16x32_bf16 v[70:73], v[208:211], v[200:203], v[70:73]
	v_mfma_f32_16x16x32_bf16 v[66:69], v[216:219], v[200:203], v[66:69]
	s_mov_b32 m0, s25
	v_lshl_add_u64 v[220:221], s[30:31], 0, v[130:131]
	s_barrier
	ds_read_b128 v[168:171], v146 offset:16384
	ds_read_b128 v[176:179], v146 offset:17408
	ds_read_b128 v[180:183], v146 offset:18432
	ds_read_b128 v[184:187], v146 offset:19456
	ds_read_b128 v[188:191], v146 offset:20480
	ds_read_b128 v[192:195], v146 offset:21504
	ds_read_b128 v[196:199], v146 offset:22528
	ds_read_b128 v[200:203], v146 offset:23552
	global_load_lds_dwordx4 v[220:221], off
	v_lshl_add_u64 v[222:223], s[30:31], 0, v[132:133]
	s_mov_b32 m0, s80
	s_nop 0
	global_load_lds_dwordx4 v[222:223], off
	s_barrier
	s_waitcnt lgkmcnt(0)
	s_waitcnt lgkmcnt(0)
	v_mfma_f32_16x16x32_bf16 v[62:65], v[148:151], v[168:171], 0
	v_mfma_f32_16x16x32_bf16 v[58:61], v[156:159], v[168:171], 0
	v_mfma_f32_16x16x32_bf16 v[46:49], v[148:151], v[180:183], 0
	v_mfma_f32_16x16x32_bf16 v[42:45], v[156:159], v[180:183], 0
	v_mfma_f32_16x16x32_bf16 v[30:33], v[148:151], v[188:191], 0
	v_mfma_f32_16x16x32_bf16 v[26:29], v[156:159], v[188:191], 0
	v_mfma_f32_16x16x32_bf16 v[14:17], v[148:151], v[196:199], 0
	v_mfma_f32_16x16x32_bf16 v[10:13], v[156:159], v[196:199], 0
	v_mfma_f32_16x16x32_bf16 v[62:65], v[152:155], v[176:179], v[62:65]
	v_mfma_f32_16x16x32_bf16 v[58:61], v[160:163], v[176:179], v[58:61]
	v_mfma_f32_16x16x32_bf16 v[46:49], v[152:155], v[184:187], v[46:49]
	v_mfma_f32_16x16x32_bf16 v[42:45], v[160:163], v[184:187], v[42:45]
	v_mfma_f32_16x16x32_bf16 v[30:33], v[152:155], v[192:195], v[30:33]
	v_mfma_f32_16x16x32_bf16 v[26:29], v[160:163], v[192:195], v[26:29]
	v_mfma_f32_16x16x32_bf16 v[14:17], v[152:155], v[200:203], v[14:17]
	v_mfma_f32_16x16x32_bf16 v[10:13], v[160:163], v[200:203], v[10:13]
	s_barrier
; #define PG8_STAGE(bufoff, gbase, voff) do { _Pragma("unroll") for (int _i = 0; _i < 2; ++_i) \
;         __builtin_amdgcn_global_load_lds((const unsigned*)((const char*)(gbase) + (voff)[_i]), (LAS unsigned*)(lds + (bufoff) + ldsw + _i * 8192), 16, 0, 0); } while (0)
; #define PG8_LDA(dst, b, h) do { _Pragma("unroll") for (int m = 0; m < 4; ++m) _Pragma("unroll") for (int k = 0; k < 2; ++k) dst[m][k] = *(const LAS bf16x8*)(lds + PG8_SA(b, h) + aoff + m * 2048 + k * 1024); } while (0)
; #define PG8_LDB(dst, b, h) do { _Pragma("unroll") for (int n = 0; n < 2; ++n) _Pragma("unroll") for (int k = 0; k < 2; ++k) dst[n][k] = *(const LAS bf16x8*)(lds + PG8_SB(b, h) + boff + n * 2048 + k * 1024); } while (0)
; #define PG8_MMA(ai, bj, At, Bt) do { __builtin_amdgcn_s_setprio(1); _Pragma("unroll") for (int m = 0; m < 4; ++m) _Pragma("unroll") for (int n = 0; n < 2; ++n) _Pragma("unroll") for (int k = 0; k < 2; ++k) \
;         acc[ai][bj][m][n] = __builtin_amdgcn_mfma_f32_16x16x32_bf16(Bt[n][k], At[m][k], acc[ai][bj][m][n], 0, 0, 0); __builtin_amdgcn_s_setprio(0); } while (0)
; #define PG8_WAIT_V(n) asm volatile("s_waitcnt vmcnt(" #n ")" ::: "memory")
; #define PG8_WAIT_L(n) asm volatile("s_waitcnt lgkmcnt(" #n ")" ::: "memory")
; #define PG8_BAR __builtin_amdgcn_s_barrier()
; #define PG8_SCHED __builtin_amdgcn_sched_barrier(0)
; template <class Epi>
; DI void gemm_phase(int wv, LAS unsigned char* lds, const GemmD g, const Epi& E) {
;     ...
;             PG8_STAGE(PG8_SB(0, 1), b2 + hstepB, voffB);
;             PG8_WAIT_V(6); PG8_BAR; PG8_MMA(1, 1, At, B1); PG8_BAR;
;             PG8_LDB(B0, 1, 0); PG8_SCHED; PG8_LDA(At, 1, 0); PG8_STAGE(PG8_SA(0, 1), a2 + hstepA, voffA);
;             PG8_WAIT_L(8); PG8_BAR; PG8_WAIT_L(0); PG8_MMA(0, 0, At, B0); PG8_BAR; PG8_SCHED;
;             PG8_LDB(B1, 1, 1); PG8_STAGE(PG8_SB(1, 0), b3, voffB);
;             PG8_BAR; PG8_WAIT_L(0); PG8_MMA(0, 1, At, B1); PG8_BAR;
;             PG8_LDA(At, 1, 1); PG8_STAGE(PG8_SA(1, 0), a3, voffA);
;             PG8_BAR; PG8_WAIT_L(0); PG8_MMA(1, 0, At, B0); PG8_BAR; PG8_SCHED;
	s_add_u32 s18, s28, 0x40000
	s_addc_u32 s19, s29, 0
	s_add_i32 s2, s2, s79
	v_lshl_add_u64 v[148:149], s[18:19], 0, v[0:1]
	s_mov_b32 m0, s2
	s_nop 0
	global_load_lds_dwordx4 v[148:149], off
	v_lshl_add_u64 v[148:149], s[18:19], 0, v[134:135]
	s_add_i32 m0, s2, 0x2000
	s_nop 0
	global_load_lds_dwordx4 v[148:149], off
	s_waitcnt vmcnt(6)
	s_barrier
	v_mfma_f32_16x16x32_bf16 v[54:57], v[204:207], v[168:171], 0
	v_mfma_f32_16x16x32_bf16 v[50:53], v[212:215], v[168:171], 0
	v_mfma_f32_16x16x32_bf16 v[38:41], v[204:207], v[180:183], 0
	v_mfma_f32_16x16x32_bf16 v[34:37], v[212:215], v[180:183], 0
	v_mfma_f32_16x16x32_bf16 v[22:25], v[204:207], v[188:191], 0
	v_mfma_f32_16x16x32_bf16 v[18:21], v[212:215], v[188:191], 0
	v_mfma_f32_16x16x32_bf16 v[6:9], v[204:207], v[196:199], 0
	v_mfma_f32_16x16x32_bf16 v[2:5], v[212:215], v[196:199], 0
	v_mfma_f32_16x16x32_bf16 v[54:57], v[208:211], v[176:179], v[54:57]
	v_mfma_f32_16x16x32_bf16 v[50:53], v[216:219], v[176:179], v[50:53]
	v_mfma_f32_16x16x32_bf16 v[38:41], v[208:211], v[184:187], v[38:41]
	v_mfma_f32_16x16x32_bf16 v[34:37], v[216:219], v[184:187], v[34:37]
	v_mfma_f32_16x16x32_bf16 v[22:25], v[208:211], v[192:195], v[22:25]
	v_mfma_f32_16x16x32_bf16 v[18:21], v[216:219], v[192:195], v[18:21]
	v_mfma_f32_16x16x32_bf16 v[6:9], v[208:211], v[200:203], v[6:9]
	v_mfma_f32_16x16x32_bf16 v[2:5], v[216:219], v[200:203], v[2:5]
	s_add_i32 s2, 0, 0x18000
	v_add_u32_e32 v147, s2, v144
	s_barrier
	ds_read_b128 v[148:151], v147
	ds_read_b128 v[152:155], v147 offset:1024
	ds_read_b128 v[156:159], v147 offset:2048
	ds_read_b128 v[160:163], v147 offset:3072
	s_add_u32 s18, s30, 0x40000
	s_addc_u32 s19, s31, 0
	s_mov_b32 m0, s81
	v_lshl_add_u64 v[204:205], s[18:19], 0, v[130:131]
	ds_read_b128 v[168:171], v146 offset:32768
	ds_read_b128 v[176:179], v146 offset:33792
	ds_read_b128 v[180:183], v146 offset:34816
	ds_read_b128 v[184:187], v146 offset:35840
	ds_read_b128 v[188:191], v146 offset:36864
	ds_read_b128 v[192:195], v146 offset:37888
	ds_read_b128 v[196:199], v146 offset:38912
	ds_read_b128 v[200:203], v146 offset:39936
	global_load_lds_dwordx4 v[204:205], off
	v_lshl_add_u64 v[204:205], s[18:19], 0, v[132:133]
	s_mov_b32 m0, s82
	s_nop 0
	global_load_lds_dwordx4 v[204:205], off
	s_waitcnt lgkmcnt(8)
	s_barrier
	s_waitcnt lgkmcnt(0)
	s_waitcnt lgkmcnt(0)
	v_mfma_f32_16x16x32_bf16 v[126:129], v[148:151], v[168:171], v[126:129]
	v_mfma_f32_16x16x32_bf16 v[122:125], v[156:159], v[168:171], v[122:125]
	v_mfma_f32_16x16x32_bf16 v[110:113], v[148:151], v[180:183], v[110:113]
	v_mfma_f32_16x16x32_bf16 v[106:109], v[156:159], v[180:183], v[106:109]
	v_mfma_f32_16x16x32_bf16 v[94:97], v[148:151], v[188:191], v[94:97]
	v_mfma_f32_16x16x32_bf16 v[90:93], v[156:159], v[188:191], v[90:93]
	v_mfma_f32_16x16x32_bf16 v[78:81], v[148:151], v[196:199], v[78:81]
	v_mfma_f32_16x16x32_bf16 v[74:77], v[156:159], v[196:199], v[74:77]
	v_mfma_f32_16x16x32_bf16 v[126:129], v[152:155], v[176:179], v[126:129]
	v_mfma_f32_16x16x32_bf16 v[122:125], v[160:163], v[176:179], v[122:125]
	v_mfma_f32_16x16x32_bf16 v[110:113], v[152:155], v[184:187], v[110:113]
	v_mfma_f32_16x16x32_bf16 v[106:109], v[160:163], v[184:187], v[106:109]
	v_mfma_f32_16x16x32_bf16 v[94:97], v[152:155], v[192:195], v[94:97]
	v_mfma_f32_16x16x32_bf16 v[90:93], v[160:163], v[192:195], v[90:93]
	v_mfma_f32_16x16x32_bf16 v[78:81], v[152:155], v[200:203], v[78:81]
	v_mfma_f32_16x16x32_bf16 v[74:77], v[160:163], v[200:203], v[74:77]
	s_barrier
	s_add_i32 s3, 0, 0x1c000
	s_add_i32 s2, s2, s79
	v_add_u32_e32 v147, s3, v144
	v_lshl_add_u64 v[140:141], v[140:141], 0, s[58:59]
	s_mov_b32 m0, s2
	ds_read_b128 v[204:207], v147
	ds_read_b128 v[208:211], v147 offset:1024
	ds_read_b128 v[212:215], v147 offset:2048
	ds_read_b128 v[216:219], v147 offset:3072
	global_load_lds_dwordx4 v[140:141], off
	v_lshl_add_u64 v[140:141], v[164:165], 0, s[58:59]
	s_add_i32 m0, s2, 0x2000
	s_nop 0
	global_load_lds_dwordx4 v[140:141], off
	s_barrier
; #define PG8_STAGE(bufoff, gbase, voff) do { _Pragma("unroll") for (int _i = 0; _i < 2; ++_i) \
;         __builtin_amdgcn_global_load_lds((const unsigned*)((const char*)(gbase) + (voff)[_i]), (LAS unsigned*)(lds + (bufoff) + ldsw + _i * 8192), 16, 0, 0); } while (0)
; #define PG8_LDA(dst, b, h) do { _Pragma("unroll") for (int m = 0; m < 4; ++m) _Pragma("unroll") for (int k = 0; k < 2; ++k) dst[m][k] = *(const LAS bf16x8*)(lds + PG8_SA(b, h) + aoff + m * 2048 + k * 1024); } while (0)
; #define PG8_LDB(dst, b, h) do { _Pragma("unroll") for (int n = 0; n < 2; ++n) _Pragma("unroll") for (int k = 0; k < 2; ++k) dst[n][k] = *(const LAS bf16x8*)(lds + PG8_SB(b, h) + boff + n * 2048 + k * 1024); } while (0)
; #define PG8_MMA(ai, bj, At, Bt) do { __builtin_amdgcn_s_setprio(1); _Pragma("unroll") for (int m = 0; m < 4; ++m) _Pragma("unroll") for (int n = 0; n < 2; ++n) _Pragma("unroll") for (int k = 0; k < 2; ++k) \
;         acc[ai][bj][m][n] = __builtin_amdgcn_mfma_f32_16x16x32_bf16(Bt[n][k], At[m][k], acc[ai][bj][m][n], 0, 0, 0); __builtin_amdgcn_s_setprio(0); } while (0)
; #define PG8_WAIT_V(n) asm volatile("s_waitcnt vmcnt(" #n ")" ::: "memory")
; #define PG8_WAIT_L(n) asm volatile("s_waitcnt lgkmcnt(" #n ")" ::: "memory")
; #define PG8_BAR __builtin_amdgcn_s_barrier()
; #define PG8_SCHED __builtin_amdgcn_sched_barrier(0)
; template <class Epi>
; DI void gemm_phase(int wv, LAS unsigned char* lds, const GemmD g, const Epi& E) {
;     ...
;             PG8_WAIT_L(8); PG8_BAR; PG8_WAIT_L(0); PG8_MMA(0, 0, At, B0); PG8_BAR; PG8_SCHED;
;             PG8_LDB(B1, 1, 1); PG8_STAGE(PG8_SB(1, 0), b3, voffB);
;             PG8_BAR; PG8_WAIT_L(0); PG8_MMA(0, 1, At, B1); PG8_BAR;
;             PG8_LDA(At, 1, 1); PG8_STAGE(PG8_SA(1, 0), a3, voffA);
;             PG8_BAR; PG8_WAIT_L(0); PG8_MMA(1, 0, At, B0); PG8_BAR; PG8_SCHED;
;             PG8_STAGE(PG8_SB(1, 1), b3 + hstepB, voffB);
;             PG8_WAIT_V(6); PG8_BAR; PG8_MMA(1, 1, At, B1); PG8_BAR;
;         }
	s_waitcnt lgkmcnt(0)
	s_waitcnt lgkmcnt(0)
	v_mfma_f32_16x16x32_bf16 v[118:121], v[204:207], v[168:171], v[118:121]
	v_mfma_f32_16x16x32_bf16 v[114:117], v[212:215], v[168:171], v[114:117]
	v_mfma_f32_16x16x32_bf16 v[102:105], v[204:207], v[180:183], v[102:105]
	v_mfma_f32_16x16x32_bf16 v[98:101], v[212:215], v[180:183], v[98:101]
	v_mfma_f32_16x16x32_bf16 v[86:89], v[204:207], v[188:191], v[86:89]
	v_mfma_f32_16x16x32_bf16 v[82:85], v[212:215], v[188:191], v[82:85]
	v_mfma_f32_16x16x32_bf16 v[70:73], v[204:207], v[196:199], v[70:73]
	v_mfma_f32_16x16x32_bf16 v[66:69], v[212:215], v[196:199], v[66:69]
	v_mfma_f32_16x16x32_bf16 v[118:121], v[208:211], v[176:179], v[118:121]
	v_mfma_f32_16x16x32_bf16 v[114:117], v[216:219], v[176:179], v[114:117]
	v_mfma_f32_16x16x32_bf16 v[102:105], v[208:211], v[184:187], v[102:105]
	v_mfma_f32_16x16x32_bf16 v[98:101], v[216:219], v[184:187], v[98:101]
	v_mfma_f32_16x16x32_bf16 v[86:89], v[208:211], v[192:195], v[86:89]
	v_mfma_f32_16x16x32_bf16 v[82:85], v[216:219], v[192:195], v[82:85]
	v_mfma_f32_16x16x32_bf16 v[70:73], v[208:211], v[200:203], v[70:73]
	v_mfma_f32_16x16x32_bf16 v[66:69], v[216:219], v[200:203], v[66:69]
	s_mov_b32 m0, s83
	v_lshl_add_u64 v[140:141], v[220:221], 0, s[58:59]
	s_barrier
	ds_read_b128 v[168:171], v146 offset:49152
	ds_read_b128 v[176:179], v146 offset:50176
	ds_read_b128 v[180:183], v146 offset:51200
	ds_read_b128 v[184:187], v146 offset:52224
	ds_read_b128 v[188:191], v146 offset:53248
	ds_read_b128 v[192:195], v146 offset:54272
	ds_read_b128 v[196:199], v146 offset:55296
	ds_read_b128 v[200:203], v146 offset:56320
	global_load_lds_dwordx4 v[140:141], off
	v_lshl_add_u64 v[140:141], v[222:223], 0, s[58:59]
	s_mov_b32 m0, s84
	s_nop 0
	global_load_lds_dwordx4 v[140:141], off
	s_barrier
	s_waitcnt lgkmcnt(0)
	s_waitcnt lgkmcnt(0)
	v_mfma_f32_16x16x32_bf16 v[62:65], v[148:151], v[168:171], v[62:65]
	v_mfma_f32_16x16x32_bf16 v[58:61], v[156:159], v[168:171], v[58:61]
	v_mfma_f32_16x16x32_bf16 v[46:49], v[148:151], v[180:183], v[46:49]
	v_mfma_f32_16x16x32_bf16 v[42:45], v[156:159], v[180:183], v[42:45]
	v_mfma_f32_16x16x32_bf16 v[30:33], v[148:151], v[188:191], v[30:33]
	v_mfma_f32_16x16x32_bf16 v[26:29], v[156:159], v[188:191], v[26:29]
	v_mfma_f32_16x16x32_bf16 v[14:17], v[148:151], v[196:199], v[14:17]
	v_mfma_f32_16x16x32_bf16 v[10:13], v[156:159], v[196:199], v[10:13]
	v_mfma_f32_16x16x32_bf16 v[62:65], v[152:155], v[176:179], v[62:65]
	v_mfma_f32_16x16x32_bf16 v[58:61], v[160:163], v[176:179], v[58:61]
	v_mfma_f32_16x16x32_bf16 v[46:49], v[152:155], v[184:187], v[46:49]
	v_mfma_f32_16x16x32_bf16 v[42:45], v[160:163], v[184:187], v[42:45]
	v_mfma_f32_16x16x32_bf16 v[30:33], v[152:155], v[192:195], v[30:33]
	v_mfma_f32_16x16x32_bf16 v[26:29], v[160:163], v[192:195], v[26:29]
	v_mfma_f32_16x16x32_bf16 v[14:17], v[152:155], v[200:203], v[14:17]
	v_mfma_f32_16x16x32_bf16 v[10:13], v[160:163], v[200:203], v[10:13]
	s_barrier
	s_add_u32 s18, s28, 0x40080
	s_addc_u32 s19, s29, 0
	s_add_i32 s2, s3, s79
	v_lshl_add_u64 v[140:141], s[18:19], 0, v[0:1]
	s_mov_b32 m0, s2
	s_nop 0
	global_load_lds_dwordx4 v[140:141], off
	v_lshl_add_u64 v[140:141], s[18:19], 0, v[134:135]
	s_add_i32 m0, s2, 0x2000
	s_nop 0
	global_load_lds_dwordx4 v[140:141], off
	s_waitcnt vmcnt(6)
	s_barrier
	v_mfma_f32_16x16x32_bf16 v[54:57], v[204:207], v[168:171], v[54:57]
	v_mfma_f32_16x16x32_bf16 v[50:53], v[212:215], v[168:171], v[50:53]
	v_mfma_f32_16x16x32_bf16 v[38:41], v[204:207], v[180:183], v[38:41]
	v_mfma_f32_16x16x32_bf16 v[34:37], v[212:215], v[180:183], v[34:37]
	v_mfma_f32_16x16x32_bf16 v[22:25], v[204:207], v[188:191], v[22:25]
	v_mfma_f32_16x16x32_bf16 v[18:21], v[212:215], v[188:191], v[18:21]
	v_mfma_f32_16x16x32_bf16 v[6:9], v[204:207], v[196:199], v[6:9]
	v_mfma_f32_16x16x32_bf16 v[2:5], v[212:215], v[196:199], v[2:5]
	v_mfma_f32_16x16x32_bf16 v[54:57], v[208:211], v[176:179], v[54:57]
	v_mfma_f32_16x16x32_bf16 v[50:53], v[216:219], v[176:179], v[50:53]
	v_mfma_f32_16x16x32_bf16 v[38:41], v[208:211], v[184:187], v[38:41]
	v_mfma_f32_16x16x32_bf16 v[34:37], v[216:219], v[184:187], v[34:37]
	v_mfma_f32_16x16x32_bf16 v[22:25], v[208:211], v[192:195], v[22:25]
	v_mfma_f32_16x16x32_bf16 v[18:21], v[216:219], v[192:195], v[18:21]
	v_mfma_f32_16x16x32_bf16 v[6:9], v[208:211], v[200:203], v[6:9]
	v_mfma_f32_16x16x32_bf16 v[2:5], v[216:219], v[200:203], v[2:5]
	s_add_i32 s41, s41, 2
	s_add_u32 s26, s26, 0x100
	s_addc_u32 s27, s27, 0
	s_add_u32 s36, s36, 0x100
	s_addc_u32 s38, s38, 0
	s_cmp_gt_u32 s41, 13
	s_barrier
	s_cbranch_scc0 .LBB0_490
	s_branch .Lgemm_epi_b
	.p2align 8

; #define PG8_STAGE(bufoff, gbase, voff) do { _Pragma("unroll") for (int _i = 0; _i < 2; ++_i) \
;         __builtin_amdgcn_global_load_lds((const unsigned*)((const char*)(gbase) + (voff)[_i]), (LAS unsigned*)(lds + (bufoff) + ldsw + _i * 8192), 16, 0, 0); } while (0)
; #define PG8_LDA(dst, b, h) do { _Pragma("unroll") for (int m = 0; m < 4; ++m) _Pragma("unroll") for (int k = 0; k < 2; ++k) dst[m][k] = *(const LAS bf16x8*)(lds + PG8_SA(b, h) + aoff + m * 2048 + k * 1024); } while (0)
; #define PG8_LDB(dst, b, h) do { _Pragma("unroll") for (int n = 0; n < 2; ++n) _Pragma("unroll") for (int k = 0; k < 2; ++k) dst[n][k] = *(const LAS bf16x8*)(lds + PG8_SB(b, h) + boff + n * 2048 + k * 1024); } while (0)
; #define PG8_WAIT_V(n) asm volatile("s_waitcnt vmcnt(" #n ")" ::: "memory")
; #define PG8_WAIT_L(n) asm volatile("s_waitcnt lgkmcnt(" #n ")" ::: "memory")
; template <class Epi>
; DI void gemm_phase(int wv, LAS unsigned char* lds, const GemmD g, const Epi& E) {
;     ...
;         const bool has_next = S.next(ui + 1, nxt);
;         const char* nA = has_next ? (const char*)g.A + (size_t)nxt.pm * 256 * g.lda * 2 : cA; const char* nB = has_next ? (const char*)g.Bt + PG8_BROW(nxt.pn) * (size_t)g.ldb * 2 : cB;
;         for (int t = 0; t < nt; t += 2) {
;             const bool last = (t == nt - 2);
;             const char* a1 = cA + (size_t)(t + 1) * kstep;
;             const char* a2 = last ? nA : cA + (size_t)(t + 2) * kstep; const char* b2 = last ? nB : cB + (size_t)(t + 2) * kstep;
;             const char* a3 = a2 + kstep; const char* b3 = b2 + kstep;
;             PG8_LDB(B0, 0, 0); PG8_SCHED; PG8_LDA(At, 0, 0); PG8_STAGE(PG8_SA(1, 1), a1 + hstepA, voffA);
;             PG8_WAIT_L(8); PG8_BAR; PG8_WAIT_L(0); PG8_MMA(0, 0, At, B0); PG8_BAR; PG8_SCHED;
;             PG8_LDB(B1, 0, 1); PG8_STAGE(PG8_SB(0, 0), b2, voffB);
;             PG8_BAR; PG8_WAIT_L(0); PG8_MMA(0, 1, At, B1); PG8_BAR;
;             PG8_LDA(At, 0, 1); PG8_STAGE(PG8_SA(0, 0), a2, voffA);
;             PG8_BAR; PG8_WAIT_L(0); PG8_MMA(1, 0, At, B0); PG8_BAR; PG8_SCHED;
;             PG8_STAGE(PG8_SB(0, 1), b2 + hstepB, voffB);
;             PG8_WAIT_V(6); PG8_BAR; PG8_MMA(1, 1, At, B1); PG8_BAR;
;             PG8_LDB(B0, 1, 0); PG8_SCHED; PG8_LDA(At, 1, 0); PG8_STAGE(PG8_SA(0, 1), a2 + hstepA, voffA);
;             PG8_WAIT_L(8); PG8_BAR; PG8_WAIT_L(0); PG8_MMA(0, 0, At, B0); PG8_BAR; PG8_SCHED;
.LBB0_543:
	s_ashr_i32 s23, s22, 31
	s_lshl_b64 s[18:19], s[22:23], s85
	v_cmp_lt_i64_e32 vcc, s[24:25], v[174:175]
	s_add_u32 s24, s81, s18
	s_addc_u32 s25, s80, s19
	s_and_b64 s[18:19], vcc, exec
	s_cselect_b32 s23, s25, s29
	s_cselect_b32 s68, s24, s28
	s_lshl_b32 s18, s55, 8
	s_ashr_i32 s19, s18, 31
	s_lshl_b64 s[18:19], s[18:19], s9
	s_add_u32 s26, s82, s18
	s_addc_u32 s27, s83, s19
	s_and_b64 s[18:19], vcc, exec
	s_cselect_b32 vcc_lo, s27, s31
	s_cselect_b32 vcc_hi, s26, s30
	s_add_u32 s28, s28, 0x80
	s_addc_u32 s29, s29, 0
	s_add_u32 s37, s30, 0x100
	s_addc_u32 s18, s31, 0
	s_mov_b32 s19, 0
	s_add_i32 s95, s19, 2
	s_add_u32 s2, s28, 0x80
	s_addc_u32 s3, s29, 0
	s_add_i32 s94, 0, 0x10000
	v_add_u32_e32 v145, s94, v141
	ds_read_b128 v[146:149], v145
	ds_read_b128 v[150:153], v145 offset:1024
	ds_read_b128 v[154:157], v145 offset:2048
	ds_read_b128 v[158:161], v145 offset:3072
	s_cmp_eq_u32 s17, s19
	s_cselect_b32 s31, s23, s3
	s_cselect_b32 s30, s68, s2
	s_cselect_b32 s35, vcc_lo, s18
	s_cselect_b32 s34, vcc_hi, s37
	v_lshl_add_u64 v[200:201], s[28:29], 0, v[136:137]
	s_add_i32 m0, s86, 0xc000
	ds_read_b128 v[162:165], v144
	ds_read_b128 v[168:171], v144 offset:1024
	ds_read_b128 v[176:179], v144 offset:2048
	ds_read_b128 v[180:183], v144 offset:3072
	ds_read_b128 v[184:187], v144 offset:4096
	ds_read_b128 v[188:191], v144 offset:5120
	ds_read_b128 v[192:195], v144 offset:6144
	ds_read_b128 v[196:199], v144 offset:7168
	global_load_lds_dwordx4 v[200:201], off
	v_lshl_add_u64 v[200:201], s[28:29], 0, v[138:139]
	s_add_i32 m0, s86, 0xe000
	s_nop 0
	global_load_lds_dwordx4 v[200:201], off
	s_waitcnt lgkmcnt(8)
	s_barrier
	s_waitcnt lgkmcnt(0)
	s_waitcnt lgkmcnt(0)
	v_mfma_f32_16x16x32_bf16 v[126:129], v[146:149], v[162:165], 0
	v_mfma_f32_16x16x32_bf16 v[122:125], v[154:157], v[162:165], 0
	v_mfma_f32_16x16x32_bf16 v[118:121], v[146:149], v[176:179], 0
	v_mfma_f32_16x16x32_bf16 v[114:117], v[154:157], v[176:179], 0
	v_mfma_f32_16x16x32_bf16 v[102:105], v[146:149], v[184:187], 0
	v_mfma_f32_16x16x32_bf16 v[98:101], v[154:157], v[184:187], 0
	v_mfma_f32_16x16x32_bf16 v[86:89], v[146:149], v[192:195], 0
	v_mfma_f32_16x16x32_bf16 v[82:85], v[154:157], v[192:195], 0
	v_mfma_f32_16x16x32_bf16 v[126:129], v[150:153], v[168:171], v[126:129]
	v_mfma_f32_16x16x32_bf16 v[122:125], v[158:161], v[168:171], v[122:125]
	v_mfma_f32_16x16x32_bf16 v[118:121], v[150:153], v[180:183], v[118:121]
	v_mfma_f32_16x16x32_bf16 v[114:117], v[158:161], v[180:183], v[114:117]
	v_mfma_f32_16x16x32_bf16 v[102:105], v[150:153], v[188:191], v[102:105]
	v_mfma_f32_16x16x32_bf16 v[98:101], v[158:161], v[188:191], v[98:101]
	v_mfma_f32_16x16x32_bf16 v[86:89], v[150:153], v[196:199], v[86:89]
	v_mfma_f32_16x16x32_bf16 v[82:85], v[158:161], v[196:199], v[82:85]
	s_barrier
	s_add_i32 s2, 0, 0x14000
	s_add_i32 s3, s94, s84
	v_add_u32_e32 v145, s2, v141
	v_lshl_add_u64 v[216:217], s[34:35], 0, v[0:1]
	s_mov_b32 m0, s3
	ds_read_b128 v[200:203], v145
	ds_read_b128 v[204:207], v145 offset:1024
	ds_read_b128 v[208:211], v145 offset:2048
	ds_read_b128 v[212:215], v145 offset:3072
	global_load_lds_dwordx4 v[216:217], off
	v_lshl_add_u64 v[218:219], s[34:35], 0, v[134:135]
	s_add_i32 m0, s3, 0x2000
	s_nop 0
	global_load_lds_dwordx4 v[218:219], off
	s_barrier
	s_waitcnt lgkmcnt(0)
	s_waitcnt lgkmcnt(0)
	v_mfma_f32_16x16x32_bf16 v[110:113], v[200:203], v[162:165], 0
	v_mfma_f32_16x16x32_bf16 v[106:109], v[208:211], v[162:165], 0
	v_mfma_f32_16x16x32_bf16 v[94:97], v[200:203], v[176:179], 0
	v_mfma_f32_16x16x32_bf16 v[90:93], v[208:211], v[176:179], 0
	v_mfma_f32_16x16x32_bf16 v[78:81], v[200:203], v[184:187], 0
	v_mfma_f32_16x16x32_bf16 v[74:77], v[208:211], v[184:187], 0
	v_mfma_f32_16x16x32_bf16 v[70:73], v[200:203], v[192:195], 0
	v_mfma_f32_16x16x32_bf16 v[66:69], v[208:211], v[192:195], 0
	v_mfma_f32_16x16x32_bf16 v[110:113], v[204:207], v[168:171], v[110:113]
	v_mfma_f32_16x16x32_bf16 v[106:109], v[212:215], v[168:171], v[106:109]
	v_mfma_f32_16x16x32_bf16 v[94:97], v[204:207], v[180:183], v[94:97]
	v_mfma_f32_16x16x32_bf16 v[90:93], v[212:215], v[180:183], v[90:93]
	v_mfma_f32_16x16x32_bf16 v[78:81], v[204:207], v[188:191], v[78:81]
	v_mfma_f32_16x16x32_bf16 v[74:77], v[212:215], v[188:191], v[74:77]
	v_mfma_f32_16x16x32_bf16 v[70:73], v[204:207], v[196:199], v[70:73]
	v_mfma_f32_16x16x32_bf16 v[66:69], v[212:215], v[196:199], v[66:69]
	s_mov_b32 m0, s86
	v_lshl_add_u64 v[220:221], s[30:31], 0, v[130:131]
	s_barrier
	ds_read_b128 v[162:165], v144 offset:16384
	ds_read_b128 v[168:171], v144 offset:17408
	ds_read_b128 v[176:179], v144 offset:18432
	ds_read_b128 v[180:183], v144 offset:19456
	ds_read_b128 v[184:187], v144 offset:20480
	ds_read_b128 v[188:191], v144 offset:21504
	ds_read_b128 v[192:195], v144 offset:22528
	ds_read_b128 v[196:199], v144 offset:23552
	global_load_lds_dwordx4 v[220:221], off
	v_lshl_add_u64 v[222:223], s[30:31], 0, v[132:133]
	s_mov_b32 m0, s87
	s_nop 0
	global_load_lds_dwordx4 v[222:223], off
	s_barrier
	s_waitcnt lgkmcnt(0)
	s_waitcnt lgkmcnt(0)
	v_mfma_f32_16x16x32_bf16 v[62:65], v[146:149], v[162:165], 0
	v_mfma_f32_16x16x32_bf16 v[58:61], v[154:157], v[162:165], 0
	v_mfma_f32_16x16x32_bf16 v[54:57], v[146:149], v[176:179], 0
	v_mfma_f32_16x16x32_bf16 v[50:53], v[154:157], v[176:179], 0
	v_mfma_f32_16x16x32_bf16 v[38:41], v[146:149], v[184:187], 0
	v_mfma_f32_16x16x32_bf16 v[34:37], v[154:157], v[184:187], 0
	v_mfma_f32_16x16x32_bf16 v[22:25], v[146:149], v[192:195], 0
	v_mfma_f32_16x16x32_bf16 v[18:21], v[154:157], v[192:195], 0
	v_mfma_f32_16x16x32_bf16 v[62:65], v[150:153], v[168:171], v[62:65]
	v_mfma_f32_16x16x32_bf16 v[58:61], v[158:161], v[168:171], v[58:61]
	v_mfma_f32_16x16x32_bf16 v[54:57], v[150:153], v[180:183], v[54:57]
	v_mfma_f32_16x16x32_bf16 v[50:53], v[158:161], v[180:183], v[50:53]
	v_mfma_f32_16x16x32_bf16 v[38:41], v[150:153], v[188:191], v[38:41]
	v_mfma_f32_16x16x32_bf16 v[34:37], v[158:161], v[188:191], v[34:37]
	v_mfma_f32_16x16x32_bf16 v[22:25], v[150:153], v[196:199], v[22:25]
	v_mfma_f32_16x16x32_bf16 v[18:21], v[158:161], v[196:199], v[18:21]
	s_barrier
; #define PG8_STAGE(bufoff, gbase, voff) do { _Pragma("unroll") for (int _i = 0; _i < 2; ++_i) \
;         __builtin_amdgcn_global_load_lds((const unsigned*)((const char*)(gbase) + (voff)[_i]), (LAS unsigned*)(lds + (bufoff) + ldsw + _i * 8192), 16, 0, 0); } while (0)
; #define PG8_LDA(dst, b, h) do { _Pragma("unroll") for (int m = 0; m < 4; ++m) _Pragma("unroll") for (int k = 0; k < 2; ++k) dst[m][k] = *(const LAS bf16x8*)(lds + PG8_SA(b, h) + aoff + m * 2048 + k * 1024); } while (0)
; #define PG8_LDB(dst, b, h) do { _Pragma("unroll") for (int n = 0; n < 2; ++n) _Pragma("unroll") for (int k = 0; k < 2; ++k) dst[n][k] = *(const LAS bf16x8*)(lds + PG8_SB(b, h) + boff + n * 2048 + k * 1024); } while (0)
; #define PG8_MMA(ai, bj, At, Bt) do { __builtin_amdgcn_s_setprio(1); _Pragma("unroll") for (int m = 0; m < 4; ++m) _Pragma("unroll") for (int n = 0; n < 2; ++n) _Pragma("unroll") for (int k = 0; k < 2; ++k) \
;         acc[ai][bj][m][n] = __builtin_amdgcn_mfma_f32_16x16x32_bf16(Bt[n][k], At[m][k], acc[ai][bj][m][n], 0, 0, 0); __builtin_amdgcn_s_setprio(0); } while (0)
; #define PG8_WAIT_V(n) asm volatile("s_waitcnt vmcnt(" #n ")" ::: "memory")
; #define PG8_WAIT_L(n) asm volatile("s_waitcnt lgkmcnt(" #n ")" ::: "memory")
; #define PG8_BAR __builtin_amdgcn_s_barrier()
; #define PG8_SCHED __builtin_amdgcn_sched_barrier(0)
; template <class Epi>
; DI void gemm_phase(int wv, LAS unsigned char* lds, const GemmD g, const Epi& E) {
;     ...
;             PG8_STAGE(PG8_SB(0, 1), b2 + hstepB, voffB);
;             PG8_WAIT_V(6); PG8_BAR; PG8_MMA(1, 1, At, B1); PG8_BAR;
;             PG8_LDB(B0, 1, 0); PG8_SCHED; PG8_LDA(At, 1, 0); PG8_STAGE(PG8_SA(0, 1), a2 + hstepA, voffA);
;             PG8_WAIT_L(8); PG8_BAR; PG8_WAIT_L(0); PG8_MMA(0, 0, At, B0); PG8_BAR; PG8_SCHED;
;             PG8_LDB(B1, 1, 1); PG8_STAGE(PG8_SB(1, 0), b3, voffB);
;             PG8_BAR; PG8_WAIT_L(0); PG8_MMA(0, 1, At, B1); PG8_BAR;
;             PG8_LDA(At, 1, 1); PG8_STAGE(PG8_SA(1, 0), a3, voffA);
;             PG8_BAR; PG8_WAIT_L(0); PG8_MMA(1, 0, At, B0); PG8_BAR; PG8_SCHED;
	s_add_u32 s34, s34, s56
	s_addc_u32 s35, s35, 0
	s_add_i32 s2, s2, s84
	v_lshl_add_u64 v[224:225], s[34:35], 0, v[0:1]
	s_mov_b32 m0, s2
	v_lshl_add_u64 v[226:227], s[34:35], 0, v[134:135]
	global_load_lds_dwordx4 v[224:225], off
	s_add_i32 m0, s2, 0x2000
	s_nop 0
	global_load_lds_dwordx4 v[226:227], off
	s_waitcnt vmcnt(6)
	s_barrier
	v_mfma_f32_16x16x32_bf16 v[46:49], v[200:203], v[162:165], 0
	v_mfma_f32_16x16x32_bf16 v[42:45], v[208:211], v[162:165], 0
	v_mfma_f32_16x16x32_bf16 v[30:33], v[200:203], v[176:179], 0
	v_mfma_f32_16x16x32_bf16 v[26:29], v[208:211], v[176:179], 0
	v_mfma_f32_16x16x32_bf16 v[14:17], v[200:203], v[184:187], 0
	v_mfma_f32_16x16x32_bf16 v[10:13], v[208:211], v[184:187], 0
	v_mfma_f32_16x16x32_bf16 v[6:9], v[200:203], v[192:195], 0
	v_mfma_f32_16x16x32_bf16 v[2:5], v[208:211], v[192:195], 0
	v_mfma_f32_16x16x32_bf16 v[46:49], v[204:207], v[168:171], v[46:49]
	v_mfma_f32_16x16x32_bf16 v[42:45], v[212:215], v[168:171], v[42:45]
	v_mfma_f32_16x16x32_bf16 v[30:33], v[204:207], v[180:183], v[30:33]
	v_mfma_f32_16x16x32_bf16 v[26:29], v[212:215], v[180:183], v[26:29]
	v_mfma_f32_16x16x32_bf16 v[14:17], v[204:207], v[188:191], v[14:17]
	v_mfma_f32_16x16x32_bf16 v[10:13], v[212:215], v[188:191], v[10:13]
	v_mfma_f32_16x16x32_bf16 v[6:9], v[204:207], v[196:199], v[6:9]
	v_mfma_f32_16x16x32_bf16 v[2:5], v[212:215], v[196:199], v[2:5]
	s_add_i32 s2, 0, 0x18000
	v_add_u32_e32 v145, s2, v141
	s_barrier
	ds_read_b128 v[146:149], v145
	ds_read_b128 v[150:153], v145 offset:1024
	ds_read_b128 v[154:157], v145 offset:2048
	ds_read_b128 v[158:161], v145 offset:3072
	s_add_u32 s30, s30, s56
	s_addc_u32 s31, s31, 0
	s_mov_b32 m0, s74
	v_lshl_add_u64 v[200:201], s[30:31], 0, v[130:131]
	ds_read_b128 v[162:165], v144 offset:32768
	ds_read_b128 v[168:171], v144 offset:33792
	ds_read_b128 v[176:179], v144 offset:34816
	ds_read_b128 v[180:183], v144 offset:35840
	ds_read_b128 v[184:187], v144 offset:36864
	ds_read_b128 v[188:191], v144 offset:37888
	ds_read_b128 v[192:195], v144 offset:38912
	ds_read_b128 v[196:199], v144 offset:39936
	global_load_lds_dwordx4 v[200:201], off
	v_lshl_add_u64 v[200:201], s[30:31], 0, v[132:133]
	s_mov_b32 m0, s41
	s_nop 0
	global_load_lds_dwordx4 v[200:201], off
	s_waitcnt lgkmcnt(8)
	s_barrier
	s_waitcnt lgkmcnt(0)
	s_waitcnt lgkmcnt(0)
	v_mfma_f32_16x16x32_bf16 v[126:129], v[146:149], v[162:165], v[126:129]
	v_mfma_f32_16x16x32_bf16 v[122:125], v[154:157], v[162:165], v[122:125]
	v_mfma_f32_16x16x32_bf16 v[118:121], v[146:149], v[176:179], v[118:121]
	v_mfma_f32_16x16x32_bf16 v[114:117], v[154:157], v[176:179], v[114:117]
	v_mfma_f32_16x16x32_bf16 v[102:105], v[146:149], v[184:187], v[102:105]
	v_mfma_f32_16x16x32_bf16 v[98:101], v[154:157], v[184:187], v[98:101]
	v_mfma_f32_16x16x32_bf16 v[86:89], v[146:149], v[192:195], v[86:89]
	v_mfma_f32_16x16x32_bf16 v[82:85], v[154:157], v[192:195], v[82:85]
	v_mfma_f32_16x16x32_bf16 v[126:129], v[150:153], v[168:171], v[126:129]
	v_mfma_f32_16x16x32_bf16 v[122:125], v[158:161], v[168:171], v[122:125]
	v_mfma_f32_16x16x32_bf16 v[118:121], v[150:153], v[180:183], v[118:121]
	v_mfma_f32_16x16x32_bf16 v[114:117], v[158:161], v[180:183], v[114:117]
	v_mfma_f32_16x16x32_bf16 v[102:105], v[150:153], v[188:191], v[102:105]
	v_mfma_f32_16x16x32_bf16 v[98:101], v[158:161], v[188:191], v[98:101]
	v_mfma_f32_16x16x32_bf16 v[86:89], v[150:153], v[196:199], v[86:89]
	v_mfma_f32_16x16x32_bf16 v[82:85], v[158:161], v[196:199], v[82:85]
	s_barrier
	s_add_i32 s3, 0, 0x1c000
	s_add_i32 s2, s2, s84
	v_add_u32_e32 v145, s3, v141
	v_lshl_add_u64 v[216:217], v[216:217], 0, s[58:59]
	s_mov_b32 m0, s2
	ds_read_b128 v[200:203], v145
	ds_read_b128 v[204:207], v145 offset:1024
	ds_read_b128 v[208:211], v145 offset:2048
	ds_read_b128 v[212:215], v145 offset:3072
	global_load_lds_dwordx4 v[216:217], off
	v_lshl_add_u64 v[216:217], v[218:219], 0, s[58:59]
	s_add_i32 m0, s2, 0x2000
	s_nop 0
	global_load_lds_dwordx4 v[216:217], off
	s_barrier
; #define PG8_STAGE(bufoff, gbase, voff) do { _Pragma("unroll") for (int _i = 0; _i < 2; ++_i) \
;         __builtin_amdgcn_global_load_lds((const unsigned*)((const char*)(gbase) + (voff)[_i]), (LAS unsigned*)(lds + (bufoff) + ldsw + _i * 8192), 16, 0, 0); } while (0)
; #define PG8_LDA(dst, b, h) do { _Pragma("unroll") for (int m = 0; m < 4; ++m) _Pragma("unroll") for (int k = 0; k < 2; ++k) dst[m][k] = *(const LAS bf16x8*)(lds + PG8_SA(b, h) + aoff + m * 2048 + k * 1024); } while (0)
; #define PG8_LDB(dst, b, h) do { _Pragma("unroll") for (int n = 0; n < 2; ++n) _Pragma("unroll") for (int k = 0; k < 2; ++k) dst[n][k] = *(const LAS bf16x8*)(lds + PG8_SB(b, h) + boff + n * 2048 + k * 1024); } while (0)
; #define PG8_MMA(ai, bj, At, Bt) do { __builtin_amdgcn_s_setprio(1); _Pragma("unroll") for (int m = 0; m < 4; ++m) _Pragma("unroll") for (int n = 0; n < 2; ++n) _Pragma("unroll") for (int k = 0; k < 2; ++k) \
;         acc[ai][bj][m][n] = __builtin_amdgcn_mfma_f32_16x16x32_bf16(Bt[n][k], At[m][k], acc[ai][bj][m][n], 0, 0, 0); __builtin_amdgcn_s_setprio(0); } while (0)
; #define PG8_WAIT_V(n) asm volatile("s_waitcnt vmcnt(" #n ")" ::: "memory")
; #define PG8_WAIT_L(n) asm volatile("s_waitcnt lgkmcnt(" #n ")" ::: "memory")
; #define PG8_BAR __builtin_amdgcn_s_barrier()
; #define PG8_SCHED __builtin_amdgcn_sched_barrier(0)
; template <class Epi>
; DI void gemm_phase(int wv, LAS unsigned char* lds, const GemmD g, const Epi& E) {
;     ...
;             PG8_WAIT_L(8); PG8_BAR; PG8_WAIT_L(0); PG8_MMA(0, 0, At, B0); PG8_BAR; PG8_SCHED;
;             PG8_LDB(B1, 1, 1); PG8_STAGE(PG8_SB(1, 0), b3, voffB);
;             PG8_BAR; PG8_WAIT_L(0); PG8_MMA(0, 1, At, B1); PG8_BAR;
;             PG8_LDA(At, 1, 1); PG8_STAGE(PG8_SA(1, 0), a3, voffA);
;             PG8_BAR; PG8_WAIT_L(0); PG8_MMA(1, 0, At, B0); PG8_BAR; PG8_SCHED;
;             PG8_STAGE(PG8_SB(1, 1), b3 + hstepB, voffB);
;             PG8_WAIT_V(6); PG8_BAR; PG8_MMA(1, 1, At, B1); PG8_BAR;
;         }
	s_waitcnt lgkmcnt(0)
	s_waitcnt lgkmcnt(0)
	v_mfma_f32_16x16x32_bf16 v[110:113], v[200:203], v[162:165], v[110:113]
	v_mfma_f32_16x16x32_bf16 v[106:109], v[208:211], v[162:165], v[106:109]
	v_mfma_f32_16x16x32_bf16 v[94:97], v[200:203], v[176:179], v[94:97]
	v_mfma_f32_16x16x32_bf16 v[90:93], v[208:211], v[176:179], v[90:93]
	v_mfma_f32_16x16x32_bf16 v[78:81], v[200:203], v[184:187], v[78:81]
	v_mfma_f32_16x16x32_bf16 v[74:77], v[208:211], v[184:187], v[74:77]
	v_mfma_f32_16x16x32_bf16 v[70:73], v[200:203], v[192:195], v[70:73]
	v_mfma_f32_16x16x32_bf16 v[66:69], v[208:211], v[192:195], v[66:69]
	v_mfma_f32_16x16x32_bf16 v[110:113], v[204:207], v[168:171], v[110:113]
	v_mfma_f32_16x16x32_bf16 v[106:109], v[212:215], v[168:171], v[106:109]
	v_mfma_f32_16x16x32_bf16 v[94:97], v[204:207], v[180:183], v[94:97]
	v_mfma_f32_16x16x32_bf16 v[90:93], v[212:215], v[180:183], v[90:93]
	v_mfma_f32_16x16x32_bf16 v[78:81], v[204:207], v[188:191], v[78:81]
	v_mfma_f32_16x16x32_bf16 v[74:77], v[212:215], v[188:191], v[74:77]
	v_mfma_f32_16x16x32_bf16 v[70:73], v[204:207], v[196:199], v[70:73]
	v_mfma_f32_16x16x32_bf16 v[66:69], v[212:215], v[196:199], v[66:69]
	s_mov_b32 m0, s13
	v_lshl_add_u64 v[216:217], v[220:221], 0, s[58:59]
	s_barrier
	ds_read_b128 v[162:165], v144 offset:49152
	ds_read_b128 v[168:171], v144 offset:50176
	ds_read_b128 v[176:179], v144 offset:51200
	ds_read_b128 v[180:183], v144 offset:52224
	ds_read_b128 v[184:187], v144 offset:53248
	ds_read_b128 v[188:191], v144 offset:54272
	ds_read_b128 v[192:195], v144 offset:55296
	ds_read_b128 v[196:199], v144 offset:56320
	global_load_lds_dwordx4 v[216:217], off
	v_lshl_add_u64 v[216:217], v[222:223], 0, s[58:59]
	s_mov_b32 m0, s16
	s_nop 0
	global_load_lds_dwordx4 v[216:217], off
	s_barrier
	s_waitcnt lgkmcnt(0)
	s_waitcnt lgkmcnt(0)
	v_mfma_f32_16x16x32_bf16 v[62:65], v[146:149], v[162:165], v[62:65]
	v_mfma_f32_16x16x32_bf16 v[58:61], v[154:157], v[162:165], v[58:61]
	v_mfma_f32_16x16x32_bf16 v[54:57], v[146:149], v[176:179], v[54:57]
	v_mfma_f32_16x16x32_bf16 v[50:53], v[154:157], v[176:179], v[50:53]
	v_mfma_f32_16x16x32_bf16 v[38:41], v[146:149], v[184:187], v[38:41]
	v_mfma_f32_16x16x32_bf16 v[34:37], v[154:157], v[184:187], v[34:37]
	v_mfma_f32_16x16x32_bf16 v[22:25], v[146:149], v[192:195], v[22:25]
	v_mfma_f32_16x16x32_bf16 v[18:21], v[154:157], v[192:195], v[18:21]
	v_mfma_f32_16x16x32_bf16 v[62:65], v[150:153], v[168:171], v[62:65]
	v_mfma_f32_16x16x32_bf16 v[58:61], v[158:161], v[168:171], v[58:61]
	v_mfma_f32_16x16x32_bf16 v[54:57], v[150:153], v[180:183], v[54:57]
	v_mfma_f32_16x16x32_bf16 v[50:53], v[158:161], v[180:183], v[50:53]
	v_mfma_f32_16x16x32_bf16 v[38:41], v[150:153], v[188:191], v[38:41]
	v_mfma_f32_16x16x32_bf16 v[34:37], v[158:161], v[188:191], v[34:37]
	v_mfma_f32_16x16x32_bf16 v[22:25], v[150:153], v[196:199], v[22:25]
	v_mfma_f32_16x16x32_bf16 v[18:21], v[158:161], v[196:199], v[18:21]
	s_barrier
	s_add_i32 s2, s3, s84
	v_lshl_add_u64 v[146:147], v[224:225], 0, s[58:59]
	s_mov_b32 m0, s2
	s_nop 0
	global_load_lds_dwordx4 v[146:147], off
	v_lshl_add_u64 v[146:147], v[226:227], 0, s[58:59]
	s_add_i32 m0, s2, 0x2000
	s_nop 0
	global_load_lds_dwordx4 v[146:147], off
	s_waitcnt vmcnt(6)
	s_barrier
	v_mfma_f32_16x16x32_bf16 v[46:49], v[200:203], v[162:165], v[46:49]
	v_mfma_f32_16x16x32_bf16 v[42:45], v[208:211], v[162:165], v[42:45]
	v_mfma_f32_16x16x32_bf16 v[30:33], v[200:203], v[176:179], v[30:33]
	v_mfma_f32_16x16x32_bf16 v[26:29], v[208:211], v[176:179], v[26:29]
	v_mfma_f32_16x16x32_bf16 v[14:17], v[200:203], v[184:187], v[14:17]
	v_mfma_f32_16x16x32_bf16 v[10:13], v[208:211], v[184:187], v[10:13]
	v_mfma_f32_16x16x32_bf16 v[6:9], v[200:203], v[192:195], v[6:9]
	v_mfma_f32_16x16x32_bf16 v[2:5], v[208:211], v[192:195], v[2:5]
	v_mfma_f32_16x16x32_bf16 v[46:49], v[204:207], v[168:171], v[46:49]
	v_mfma_f32_16x16x32_bf16 v[42:45], v[212:215], v[168:171], v[42:45]
	v_mfma_f32_16x16x32_bf16 v[30:33], v[204:207], v[180:183], v[30:33]
	v_mfma_f32_16x16x32_bf16 v[26:29], v[212:215], v[180:183], v[26:29]
	v_mfma_f32_16x16x32_bf16 v[14:17], v[204:207], v[188:191], v[14:17]
	v_mfma_f32_16x16x32_bf16 v[10:13], v[212:215], v[188:191], v[10:13]
	v_mfma_f32_16x16x32_bf16 v[6:9], v[204:207], v[196:199], v[6:9]
	v_mfma_f32_16x16x32_bf16 v[2:5], v[212:215], v[196:199], v[2:5]
	s_add_u32 s28, s28, 0x100
	s_addc_u32 s29, s29, 0
	s_add_u32 s37, s37, 0x100
	s_addc_u32 s18, s18, 0
	s_cmp_ge_u32 s95, s38
	s_mov_b32 s19, s95
	s_barrier
	s_cbranch_scc0 .LBB0_544
	s_branch .Lgemm_epi_c
	.p2align 8
